# v76 + poll tightening: s_sleep 1/2 in all barrier / hand-off / flag poll loops reduced to s_sleep 0 (shorter release-detection latency)
# baseline (speedup 1.0000x reference)
; __global__ void __launch_bounds__(NTHREADS, 2) fwd_megakernel(Params p) {
;     ...
;     if (ws == nullptr) grid.sync();
.LBB0_12:
	s_sleep 0
	global_load_dword v3, v2, s[6:7] offset:32 sc1
	s_waitcnt vmcnt(0)
	v_and_b32_e32 v3, 0xffff0000, v3
	v_cmp_ne_u32_e32 vcc, v3, v1
	s_or_b64 s[8:9], vcc, s[8:9]
	s_andn2_b64 exec, exec, s[8:9]
	s_cbranch_execnz .LBB0_12

; __device__ __forceinline__ unsigned xb_ld(unsigned* p)              { return __hip_atomic_load(p, __ATOMIC_RELAXED, __HIP_MEMORY_SCOPE_AGENT); }
; __device__ __forceinline__ void xcd_barrier_complete(unsigned* bar, unsigned x, unsigned& nloc, unsigned& nx) {
;     ...
;     for (;;) {
;         sum = 0u; cnt = 0u; mine = 0u;
; #pragma unroll
;         for (unsigned j = 0; j < 16; ++j) { const unsigned c = xb_ld(&bar[XB_XCNT(j)]); sum += c; cnt += (c > 0u) ? 1u : 0u; mine = (j == x) ? c : mine; }
;         if (sum == G) break;
;         __builtin_amdgcn_s_sleep(1);
;         if ((++sp & 255u) == 0u) { if (xb_ld(&bar[XB_TMO])) break; if (sp > XB_SPIN_CAP) { atomicAdd(&bar[XB_TMO], 1u); break; } }
;     }
.LBB0_40:
	global_load_dword v15, v16, s[8:9] sc1
	s_waitcnt lgkmcnt(0)
	global_load_dword v0, v16, s[10:11] sc1
	global_load_dword v1, v16, s[12:13] sc1
	global_load_dword v2, v16, s[14:15] sc1
	global_load_dword v3, v16, s[40:41] sc1
	global_load_dword v4, v16, s[42:43] sc1
	global_load_dword v5, v16, s[82:83] sc1
	global_load_dword v6, v16, s[92:93] sc1
	global_load_dword v7, v16, s[94:95] sc1
	global_load_dword v8, v16, s[96:97] sc1
	global_load_dword v9, v16, s[90:91] sc1
	global_load_dword v10, v16, s[0:1] sc1
	global_load_dword v11, v16, s[88:89] sc1
	global_load_dword v12, v16, s[52:53] sc1
	global_load_dword v13, v16, s[54:55] sc1
	global_load_dword v14, v16, s[56:57] sc1
	s_mov_b64 s[58:59], -1
	s_mov_b64 s[60:61], -1
	s_waitcnt vmcnt(14)
	v_add_u32_e32 v17, v0, v15
	s_waitcnt vmcnt(13)
	v_add_u32_e32 v17, v17, v1
	s_waitcnt vmcnt(12)
	v_add_u32_e32 v17, v17, v2
	s_waitcnt vmcnt(11)
	v_add_u32_e32 v17, v17, v3
	s_waitcnt vmcnt(10)
	v_add_u32_e32 v17, v17, v4
	s_waitcnt vmcnt(9)
	v_add_u32_e32 v17, v17, v5
	s_waitcnt vmcnt(8)
	v_add_u32_e32 v17, v17, v6
	s_waitcnt vmcnt(7)
	v_add_u32_e32 v17, v17, v7
	s_waitcnt vmcnt(6)
	v_add_u32_e32 v17, v17, v8
	s_waitcnt vmcnt(5)
	v_add_u32_e32 v17, v17, v9
	s_waitcnt vmcnt(4)
	v_add_u32_e32 v17, v17, v10
	s_waitcnt vmcnt(3)
	v_add_u32_e32 v17, v17, v11
	s_waitcnt vmcnt(2)
	v_add_u32_e32 v17, v17, v12
	s_waitcnt vmcnt(1)
	v_add_u32_e32 v17, v17, v13
	s_waitcnt vmcnt(0)
	v_add_u32_e32 v17, v17, v14
	v_cmp_eq_u32_e32 vcc, s3, v17
	s_cbranch_vccnz .LBB0_39
	s_and_b32 s35, s33, 0xff
	s_cmp_eq_u32 s35, 0
	s_mov_b64 s[62:63], -1
	s_sleep 0
	s_cbranch_scc1 .LBB0_44
	s_and_b64 vcc, exec, s[62:63]
	s_cbranch_vccz .LBB0_39

; __device__ __forceinline__ unsigned xb_ld(unsigned* p)              { return __hip_atomic_load(p, __ATOMIC_RELAXED, __HIP_MEMORY_SCOPE_AGENT); }
; #define XB_SPIN(cond, bar) do { unsigned _sp = 0; while (cond) { __builtin_amdgcn_s_sleep(1); \
;     if ((++_sp & 255u) == 0u) { if (xb_ld(&(bar)[XB_TMO])) break; if (_sp > XB_SPIN_CAP) { atomicAdd(&(bar)[XB_TMO], 1u); break; } } } } while (0)
; __device__ __forceinline__ void xcd_barrier(const XcdBarrier& b) {
;     ...
;             else XB_SPIN(xb_ld(&bar[XB_TOPGEN]) == tg, bar);
.LBB0_58:
	s_and_b32 s33, s3, 0xff
	s_mov_b64 s[42:43], -1
	s_cmp_lg_u32 s33, 0
	s_mov_b64 s[54:55], -1
	s_sleep 0
	s_cbranch_scc0 .LBB0_61
	s_and_b64 vcc, exec, s[54:55]
	s_cbranch_vccz .LBB0_57

; __device__ __forceinline__ unsigned xb_ld(unsigned* p)              { return __hip_atomic_load(p, __ATOMIC_RELAXED, __HIP_MEMORY_SCOPE_AGENT); }
; #define XB_SPIN(cond, bar) do { unsigned _sp = 0; while (cond) { __builtin_amdgcn_s_sleep(1); \
;     if ((++_sp & 255u) == 0u) { if (xb_ld(&(bar)[XB_TMO])) break; if (_sp > XB_SPIN_CAP) { atomicAdd(&(bar)[XB_TMO], 1u); break; } } } } while (0)
; __device__ __forceinline__ void xcd_barrier(const XcdBarrier& b) {
;     ...
;             XB_SPIN(xb_ld(&bar[XB_XGEN(b.x)]) == gen, bar);
.LBB0_75:
	s_and_b32 s33, s3, 0xff
	s_cmp_lg_u32 s33, 0
	s_mov_b64 s[52:53], -1
	s_sleep 0
	s_cbranch_scc0 .LBB0_78
	s_mov_b64 s[54:55], -1
	s_and_b64 vcc, exec, s[52:53]
	s_cbranch_vccz .LBB0_74

; __global__ void __launch_bounds__(NTHREADS, 2) fwd_megakernel(Params p) {
;     ...
;     if (threadIdx.x == 0) { unsigned* f = (unsigned*)(ws + WS_BAR) + ADA_FLAG; unsigned sp = 0;
;         while (__hip_atomic_load(f, __ATOMIC_RELAXED, __HIP_MEMORY_SCOPE_AGENT) < 48u) { __builtin_amdgcn_s_sleep(2); if (++sp > (1u << 20)) break; }
;         __builtin_amdgcn_fence(__ATOMIC_ACQUIRE, "agent"); asm volatile("s_waitcnt vmcnt(0)" ::: "memory"); }
.LBB0_155:
	global_load_dword v1, v0, s[4:5] sc1
	s_mov_b64 s[0:1], -1
	s_waitcnt vmcnt(0)
	v_cmp_lt_u32_e32 vcc, 47, v1
	s_cbranch_vccnz .LBB0_154
	s_cmp_lg_u32 s3, 0
	s_sleep 0
	s_cbranch_scc0 .LBB0_153
	global_load_dword v1, v0, s[4:5] sc1
	s_waitcnt vmcnt(0)
	v_cmp_gt_u32_e32 vcc, 48, v1
	s_cbranch_vccz .LBB0_154
	s_sleep 0
	global_load_dword v1, v0, s[4:5] sc1
	s_waitcnt vmcnt(0)
	v_cmp_gt_u32_e32 vcc, 48, v1
	s_cbranch_vccz .LBB0_154
	s_sleep 0
	global_load_dword v1, v0, s[4:5] sc1
	s_waitcnt vmcnt(0)
	v_cmp_gt_u32_e32 vcc, 48, v1
	s_cbranch_vccz .LBB0_154
	s_sleep 0
	global_load_dword v1, v0, s[4:5] sc1
	s_waitcnt vmcnt(0)
	v_cmp_gt_u32_e32 vcc, 48, v1
	s_cbranch_vccz .LBB0_154
	s_sleep 0
	global_load_dword v1, v0, s[4:5] sc1
	s_waitcnt vmcnt(0)
	v_cmp_gt_u32_e32 vcc, 48, v1
	s_cbranch_vccz .LBB0_154
	s_sleep 0
	global_load_dword v1, v0, s[4:5] sc1
	s_waitcnt vmcnt(0)
	v_cmp_gt_u32_e32 vcc, 48, v1
	s_cbranch_vccz .LBB0_154
	s_sleep 0
	global_load_dword v1, v0, s[4:5] sc1
	s_waitcnt vmcnt(0)
	v_cmp_gt_u32_e32 vcc, 48, v1
	s_cbranch_vccz .LBB0_154
	s_sleep 0
	s_add_i32 s3, s3, -8
	s_mov_b64 s[0:1], 0
	s_branch .LBB0_154

; __device__ __forceinline__ unsigned xb_ld(unsigned* p)              { return __hip_atomic_load(p, __ATOMIC_RELAXED, __HIP_MEMORY_SCOPE_AGENT); }
; __device__ __forceinline__ void xcd_barrier_complete(unsigned* bar, unsigned x, unsigned& nloc, unsigned& nx) {
;     ...
;     for (;;) {
;         sum = 0u; cnt = 0u; mine = 0u;
; #pragma unroll
;         for (unsigned j = 0; j < 16; ++j) { const unsigned c = xb_ld(&bar[XB_XCNT(j)]); sum += c; cnt += (c > 0u) ? 1u : 0u; mine = (j == x) ? c : mine; }
;         if (sum == G) break;
;         __builtin_amdgcn_s_sleep(1);
;         if ((++sp & 255u) == 0u) { if (xb_ld(&bar[XB_TMO])) break; if (sp > XB_SPIN_CAP) { atomicAdd(&bar[XB_TMO], 1u); break; } }
;     }
.LBB0_178:
	global_load_dword v15, v16, s[8:9] sc1
	s_waitcnt lgkmcnt(0)
	global_load_dword v0, v16, s[10:11] sc1
	global_load_dword v1, v16, s[12:13] sc1
	global_load_dword v2, v16, s[14:15] sc1
	global_load_dword v3, v16, s[18:19] sc1
	global_load_dword v4, v16, s[40:41] sc1
	global_load_dword v5, v16, s[42:43] sc1
	global_load_dword v6, v16, s[54:55] sc1
	global_load_dword v7, v16, s[56:57] sc1
	global_load_dword v8, v16, s[58:59] sc1
	global_load_dword v9, v16, s[60:61] sc1
	global_load_dword v10, v16, s[0:1] sc1
	global_load_dword v11, v16, s[62:63] sc1
	global_load_dword v12, v16, s[52:53] sc1
	global_load_dword v13, v16, s[64:65] sc1
	global_load_dword v14, v16, s[66:67] sc1
	s_mov_b64 s[74:75], -1
	s_mov_b64 s[78:79], -1
	s_waitcnt vmcnt(14)
	v_add_u32_e32 v17, v0, v15
	s_waitcnt vmcnt(13)
	v_add_u32_e32 v17, v17, v1
	s_waitcnt vmcnt(12)
	v_add_u32_e32 v17, v17, v2
	s_waitcnt vmcnt(11)
	v_add_u32_e32 v17, v17, v3
	s_waitcnt vmcnt(10)
	v_add_u32_e32 v17, v17, v4
	s_waitcnt vmcnt(9)
	v_add_u32_e32 v17, v17, v5
	s_waitcnt vmcnt(8)
	v_add_u32_e32 v17, v17, v6
	s_waitcnt vmcnt(7)
	v_add_u32_e32 v17, v17, v7
	s_waitcnt vmcnt(6)
	v_add_u32_e32 v17, v17, v8
	s_waitcnt vmcnt(5)
	v_add_u32_e32 v17, v17, v9
	s_waitcnt vmcnt(4)
	v_add_u32_e32 v17, v17, v10
	s_waitcnt vmcnt(3)
	v_add_u32_e32 v17, v17, v11
	s_waitcnt vmcnt(2)
	v_add_u32_e32 v17, v17, v12
	s_waitcnt vmcnt(1)
	v_add_u32_e32 v17, v17, v13
	s_waitcnt vmcnt(0)
	v_add_u32_e32 v17, v17, v14
	v_cmp_eq_u32_e32 vcc, s3, v17
	s_cbranch_vccnz .LBB0_177
	s_and_b32 s17, s16, 0xff
	s_cmp_eq_u32 s17, 0
	s_mov_b64 s[82:83], -1
	s_sleep 0
	s_cbranch_scc1 .LBB0_182
	s_and_b64 vcc, exec, s[82:83]
	s_cbranch_vccz .LBB0_177

; __device__ __forceinline__ unsigned xb_ld(unsigned* p)              { return __hip_atomic_load(p, __ATOMIC_RELAXED, __HIP_MEMORY_SCOPE_AGENT); }
; #define XB_SPIN(cond, bar) do { unsigned _sp = 0; while (cond) { __builtin_amdgcn_s_sleep(1); \
;     if ((++_sp & 255u) == 0u) { if (xb_ld(&(bar)[XB_TMO])) break; if (_sp > XB_SPIN_CAP) { atomicAdd(&(bar)[XB_TMO], 1u); break; } } } } while (0)
; __device__ __forceinline__ void xcd_barrier(const XcdBarrier& b) {
;     ...
;             else XB_SPIN(xb_ld(&bar[XB_TOPGEN]) == tg, bar);
.LBB0_196:
	s_and_b32 s16, s3, 0xff
	s_mov_b64 s[40:41], -1
	s_cmp_lg_u32 s16, 0
	s_mov_b64 s[52:53], -1
	s_sleep 0
	s_cbranch_scc0 .LBB0_199
	s_and_b64 vcc, exec, s[52:53]
	s_cbranch_vccz .LBB0_195

; __device__ __forceinline__ unsigned xb_ld(unsigned* p)              { return __hip_atomic_load(p, __ATOMIC_RELAXED, __HIP_MEMORY_SCOPE_AGENT); }
; #define XB_SPIN(cond, bar) do { unsigned _sp = 0; while (cond) { __builtin_amdgcn_s_sleep(1); \
;     if ((++_sp & 255u) == 0u) { if (xb_ld(&(bar)[XB_TMO])) break; if (_sp > XB_SPIN_CAP) { atomicAdd(&(bar)[XB_TMO], 1u); break; } } } } while (0)
; __device__ __forceinline__ void xcd_barrier(const XcdBarrier& b) {
;     ...
;             XB_SPIN(xb_ld(&bar[XB_XGEN(b.x)]) == gen, bar);
.LBB0_213:
	s_and_b32 s16, s3, 0xff
	s_cmp_lg_u32 s16, 0
	s_mov_b64 s[42:43], -1
	s_sleep 0
	s_cbranch_scc0 .LBB0_216
	s_mov_b64 s[52:53], -1
	s_and_b64 vcc, exec, s[42:43]
	s_cbranch_vccz .LBB0_212

; __device__ __forceinline__ unsigned xb_ld(unsigned* p)              { return __hip_atomic_load(p, __ATOMIC_RELAXED, __HIP_MEMORY_SCOPE_AGENT); }
; __device__ __forceinline__ void xcd_barrier_complete(unsigned* bar, unsigned x, unsigned& nloc, unsigned& nx) {
;     ...
;     for (;;) {
;         sum = 0u; cnt = 0u; mine = 0u;
; #pragma unroll
;         for (unsigned j = 0; j < 16; ++j) { const unsigned c = xb_ld(&bar[XB_XCNT(j)]); sum += c; cnt += (c > 0u) ? 1u : 0u; mine = (j == x) ? c : mine; }
;         if (sum == G) break;
;         __builtin_amdgcn_s_sleep(1);
;         if ((++sp & 255u) == 0u) { if (xb_ld(&bar[XB_TMO])) break; if (sp > XB_SPIN_CAP) { atomicAdd(&bar[XB_TMO], 1u); break; } }
;     }
.LBB0_276:
	global_load_dword v15, v16, s[8:9] sc1
	s_waitcnt lgkmcnt(0)
	global_load_dword v0, v16, s[10:11] sc1
	global_load_dword v1, v16, s[12:13] sc1
	global_load_dword v2, v16, s[14:15] sc1
	global_load_dword v3, v16, s[18:19] sc1
	global_load_dword v4, v16, s[54:55] sc1
	global_load_dword v5, v16, s[56:57] sc1
	global_load_dword v6, v16, s[58:59] sc1
	global_load_dword v7, v16, s[60:61] sc1
	global_load_dword v8, v16, s[62:63] sc1
	global_load_dword v9, v16, s[66:67] sc1
	global_load_dword v10, v16, s[0:1] sc1
	global_load_dword v11, v16, s[74:75] sc1
	global_load_dword v12, v16, s[52:53] sc1
	global_load_dword v13, v16, s[64:65] sc1
	global_load_dword v14, v16, s[78:79] sc1
	s_mov_b64 s[82:83], -1
	s_mov_b64 s[88:89], -1
	s_waitcnt vmcnt(14)
	v_add_u32_e32 v17, v0, v15
	s_waitcnt vmcnt(13)
	v_add_u32_e32 v17, v17, v1
	s_waitcnt vmcnt(12)
	v_add_u32_e32 v17, v17, v2
	s_waitcnt vmcnt(11)
	v_add_u32_e32 v17, v17, v3
	s_waitcnt vmcnt(10)
	v_add_u32_e32 v17, v17, v4
	s_waitcnt vmcnt(9)
	v_add_u32_e32 v17, v17, v5
	s_waitcnt vmcnt(8)
	v_add_u32_e32 v17, v17, v6
	s_waitcnt vmcnt(7)
	v_add_u32_e32 v17, v17, v7
	s_waitcnt vmcnt(6)
	v_add_u32_e32 v17, v17, v8
	s_waitcnt vmcnt(5)
	v_add_u32_e32 v17, v17, v9
	s_waitcnt vmcnt(4)
	v_add_u32_e32 v17, v17, v10
	s_waitcnt vmcnt(3)
	v_add_u32_e32 v17, v17, v11
	s_waitcnt vmcnt(2)
	v_add_u32_e32 v17, v17, v12
	s_waitcnt vmcnt(1)
	v_add_u32_e32 v17, v17, v13
	s_waitcnt vmcnt(0)
	v_add_u32_e32 v17, v17, v14
	v_cmp_eq_u32_e32 vcc, s3, v17
	s_cbranch_vccnz .LBB0_275
	s_and_b32 s17, s16, 0xff
	s_cmp_eq_u32 s17, 0
	s_mov_b64 s[90:91], -1
	s_sleep 0
	s_cbranch_scc1 .LBB0_280
	s_and_b64 vcc, exec, s[90:91]
	s_cbranch_vccz .LBB0_275

; __device__ __forceinline__ unsigned xb_ld(unsigned* p)              { return __hip_atomic_load(p, __ATOMIC_RELAXED, __HIP_MEMORY_SCOPE_AGENT); }
; #define XB_SPIN(cond, bar) do { unsigned _sp = 0; while (cond) { __builtin_amdgcn_s_sleep(1); \
;     if ((++_sp & 255u) == 0u) { if (xb_ld(&(bar)[XB_TMO])) break; if (_sp > XB_SPIN_CAP) { atomicAdd(&(bar)[XB_TMO], 1u); break; } } } } while (0)
; __device__ __forceinline__ void xcd_barrier(const XcdBarrier& b) {
;     ...
;             else XB_SPIN(xb_ld(&bar[XB_TOPGEN]) == tg, bar);
.LBB0_294:
	s_and_b32 s16, s3, 0xff
	s_mov_b64 s[52:53], -1
	s_cmp_lg_u32 s16, 0
	s_mov_b64 s[56:57], -1
	s_sleep 0
	s_cbranch_scc0 .LBB0_297
	s_and_b64 vcc, exec, s[56:57]
	s_cbranch_vccz .LBB0_293

; __device__ __forceinline__ unsigned xb_ld(unsigned* p)              { return __hip_atomic_load(p, __ATOMIC_RELAXED, __HIP_MEMORY_SCOPE_AGENT); }
; #define XB_SPIN(cond, bar) do { unsigned _sp = 0; while (cond) { __builtin_amdgcn_s_sleep(1); \
;     if ((++_sp & 255u) == 0u) { if (xb_ld(&(bar)[XB_TMO])) break; if (_sp > XB_SPIN_CAP) { atomicAdd(&(bar)[XB_TMO], 1u); break; } } } } while (0)
; __device__ __forceinline__ void xcd_barrier(const XcdBarrier& b) {
;     ...
;             XB_SPIN(xb_ld(&bar[XB_XGEN(b.x)]) == gen, bar);
.LBB0_311:
	s_and_b32 s16, s3, 0xff
	s_cmp_lg_u32 s16, 0
	s_mov_b64 s[54:55], -1
	s_sleep 0
	s_cbranch_scc0 .LBB0_314
	s_mov_b64 s[56:57], -1
	s_and_b64 vcc, exec, s[54:55]
	s_cbranch_vccz .LBB0_310

; __device__ __forceinline__ unsigned xb_ld(unsigned* p)              { return __hip_atomic_load(p, __ATOMIC_RELAXED, __HIP_MEMORY_SCOPE_AGENT); }
; __device__ __forceinline__ void xcd_barrier_complete(unsigned* bar, unsigned x, unsigned& nloc, unsigned& nx) {
;     ...
;     for (;;) {
;         sum = 0u; cnt = 0u; mine = 0u;
; #pragma unroll
;         for (unsigned j = 0; j < 16; ++j) { const unsigned c = xb_ld(&bar[XB_XCNT(j)]); sum += c; cnt += (c > 0u) ? 1u : 0u; mine = (j == x) ? c : mine; }
;         if (sum == G) break;
;         __builtin_amdgcn_s_sleep(1);
;         if ((++sp & 255u) == 0u) { if (xb_ld(&bar[XB_TMO])) break; if (sp > XB_SPIN_CAP) { atomicAdd(&bar[XB_TMO], 1u); break; } }
;     }
.LBB0_480:
	global_load_dword v15, v16, s[12:13] sc1
	s_waitcnt lgkmcnt(0)
	global_load_dword v0, v16, s[14:15] sc1
	global_load_dword v1, v16, s[18:19] sc1
	global_load_dword v2, v16, s[44:45] sc1
	global_load_dword v3, v16, s[46:47] sc1
	global_load_dword v4, v16, s[56:57] sc1
	global_load_dword v5, v16, s[58:59] sc1
	global_load_dword v6, v16, s[60:61] sc1
	global_load_dword v7, v16, s[62:63] sc1
	global_load_dword v8, v16, s[66:67] sc1
	global_load_dword v9, v16, s[70:71] sc1
	global_load_dword v10, v16, s[0:1] sc1
	global_load_dword v11, v16, s[72:73] sc1
	global_load_dword v12, v16, s[52:53] sc1
	global_load_dword v13, v16, s[64:65] sc1
	global_load_dword v14, v16, s[74:75] sc1
	s_mov_b64 s[78:79], -1
	s_mov_b64 s[82:83], -1
	s_waitcnt vmcnt(14)
	v_add_u32_e32 v17, v0, v15
	s_waitcnt vmcnt(13)
	v_add_u32_e32 v17, v17, v1
	s_waitcnt vmcnt(12)
	v_add_u32_e32 v17, v17, v2
	s_waitcnt vmcnt(11)
	v_add_u32_e32 v17, v17, v3
	s_waitcnt vmcnt(10)
	v_add_u32_e32 v17, v17, v4
	s_waitcnt vmcnt(9)
	v_add_u32_e32 v17, v17, v5
	s_waitcnt vmcnt(8)
	v_add_u32_e32 v17, v17, v6
	s_waitcnt vmcnt(7)
	v_add_u32_e32 v17, v17, v7
	s_waitcnt vmcnt(6)
	v_add_u32_e32 v17, v17, v8
	s_waitcnt vmcnt(5)
	v_add_u32_e32 v17, v17, v9
	s_waitcnt vmcnt(4)
	v_add_u32_e32 v17, v17, v10
	s_waitcnt vmcnt(3)
	v_add_u32_e32 v17, v17, v11
	s_waitcnt vmcnt(2)
	v_add_u32_e32 v17, v17, v12
	s_waitcnt vmcnt(1)
	v_add_u32_e32 v17, v17, v13
	s_waitcnt vmcnt(0)
	v_add_u32_e32 v17, v17, v14
	v_cmp_eq_u32_e32 vcc, s4, v17
	s_cbranch_vccnz .LBB0_479
	s_and_b32 s16, s5, 0xff
	s_cmp_eq_u32 s16, 0
	s_mov_b64 s[88:89], -1
	s_sleep 0
	s_cbranch_scc1 .LBB0_484
	s_and_b64 vcc, exec, s[88:89]
	s_cbranch_vccz .LBB0_479

; __device__ __forceinline__ unsigned xb_ld(unsigned* p)              { return __hip_atomic_load(p, __ATOMIC_RELAXED, __HIP_MEMORY_SCOPE_AGENT); }
; #define XB_SPIN(cond, bar) do { unsigned _sp = 0; while (cond) { __builtin_amdgcn_s_sleep(1); \
;     if ((++_sp & 255u) == 0u) { if (xb_ld(&(bar)[XB_TMO])) break; if (_sp > XB_SPIN_CAP) { atomicAdd(&(bar)[XB_TMO], 1u); break; } } } } while (0)
; __device__ __forceinline__ void xcd_barrier(const XcdBarrier& b) {
;     ...
;             else XB_SPIN(xb_ld(&bar[XB_TOPGEN]) == tg, bar);
.LBB0_498:
	s_and_b32 s5, s4, 0xff
	s_mov_b64 s[52:53], -1
	s_cmp_lg_u32 s5, 0
	s_mov_b64 s[58:59], -1
	s_sleep 0
	s_cbranch_scc0 .LBB0_501
	s_and_b64 vcc, exec, s[58:59]
	s_cbranch_vccz .LBB0_497

; __device__ __forceinline__ unsigned xb_ld(unsigned* p)              { return __hip_atomic_load(p, __ATOMIC_RELAXED, __HIP_MEMORY_SCOPE_AGENT); }
; #define XB_SPIN(cond, bar) do { unsigned _sp = 0; while (cond) { __builtin_amdgcn_s_sleep(1); \
;     if ((++_sp & 255u) == 0u) { if (xb_ld(&(bar)[XB_TMO])) break; if (_sp > XB_SPIN_CAP) { atomicAdd(&(bar)[XB_TMO], 1u); break; } } } } while (0)
; __device__ __forceinline__ void xcd_barrier(const XcdBarrier& b) {
;     ...
;             XB_SPIN(xb_ld(&bar[XB_XGEN(b.x)]) == gen, bar);
.LBB0_515:
	s_and_b32 s5, s4, 0xff
	s_cmp_lg_u32 s5, 0
	s_mov_b64 s[56:57], -1
	s_sleep 0
	s_cbranch_scc0 .LBB0_518
	s_mov_b64 s[58:59], -1
	s_and_b64 vcc, exec, s[56:57]
	s_cbranch_vccz .LBB0_514

; __device__ __forceinline__ unsigned xb_ld(unsigned* p)              { return __hip_atomic_load(p, __ATOMIC_RELAXED, __HIP_MEMORY_SCOPE_AGENT); }
; __device__ __forceinline__ void xcd_barrier_complete(unsigned* bar, unsigned x, unsigned& nloc, unsigned& nx) {
;     ...
;     for (;;) {
;         sum = 0u; cnt = 0u; mine = 0u;
; #pragma unroll
;         for (unsigned j = 0; j < 16; ++j) { const unsigned c = xb_ld(&bar[XB_XCNT(j)]); sum += c; cnt += (c > 0u) ? 1u : 0u; mine = (j == x) ? c : mine; }
;         if (sum == G) break;
;         __builtin_amdgcn_s_sleep(1);
;         if ((++sp & 255u) == 0u) { if (xb_ld(&bar[XB_TMO])) break; if (sp > XB_SPIN_CAP) { atomicAdd(&bar[XB_TMO], 1u); break; } }
;     }
.LBB0_810:
	global_load_dword v15, v16, s[10:11] sc1
	s_waitcnt lgkmcnt(0)
	global_load_dword v0, v16, s[12:13] sc1
	global_load_dword v1, v16, s[14:15] sc1
	global_load_dword v2, v16, s[18:19] sc1
	global_load_dword v3, v16, s[56:57] sc1
	global_load_dword v4, v16, s[58:59] sc1
	global_load_dword v5, v16, s[60:61] sc1
	global_load_dword v6, v16, s[62:63] sc1
	global_load_dword v7, v16, s[66:67] sc1
	global_load_dword v8, v16, s[68:69] sc1
	global_load_dword v9, v16, s[70:71] sc1
	global_load_dword v10, v16, s[0:1] sc1
	global_load_dword v11, v16, s[72:73] sc1
	global_load_dword v12, v16, s[52:53] sc1
	global_load_dword v13, v16, s[64:65] sc1
	global_load_dword v14, v16, s[74:75] sc1
	s_mov_b64 s[76:77], -1
	s_mov_b64 s[78:79], -1
	s_waitcnt vmcnt(14)
	v_add_u32_e32 v17, v0, v15
	s_waitcnt vmcnt(13)
	v_add_u32_e32 v17, v17, v1
	s_waitcnt vmcnt(12)
	v_add_u32_e32 v17, v17, v2
	s_waitcnt vmcnt(11)
	v_add_u32_e32 v17, v17, v3
	s_waitcnt vmcnt(10)
	v_add_u32_e32 v17, v17, v4
	s_waitcnt vmcnt(9)
	v_add_u32_e32 v17, v17, v5
	s_waitcnt vmcnt(8)
	v_add_u32_e32 v17, v17, v6
	s_waitcnt vmcnt(7)
	v_add_u32_e32 v17, v17, v7
	s_waitcnt vmcnt(6)
	v_add_u32_e32 v17, v17, v8
	s_waitcnt vmcnt(5)
	v_add_u32_e32 v17, v17, v9
	s_waitcnt vmcnt(4)
	v_add_u32_e32 v17, v17, v10
	s_waitcnt vmcnt(3)
	v_add_u32_e32 v17, v17, v11
	s_waitcnt vmcnt(2)
	v_add_u32_e32 v17, v17, v12
	s_waitcnt vmcnt(1)
	v_add_u32_e32 v17, v17, v13
	s_waitcnt vmcnt(0)
	v_add_u32_e32 v17, v17, v14
	v_cmp_eq_u32_e32 vcc, s4, v17
	s_cbranch_vccnz .LBB0_809
	s_and_b32 s16, s5, 0xff
	s_cmp_eq_u32 s16, 0
	s_mov_b64 s[80:81], -1
	s_sleep 0
	s_cbranch_scc1 .LBB0_814
	s_and_b64 vcc, exec, s[80:81]
	s_cbranch_vccz .LBB0_809

; __device__ __forceinline__ unsigned xb_ld(unsigned* p)              { return __hip_atomic_load(p, __ATOMIC_RELAXED, __HIP_MEMORY_SCOPE_AGENT); }
; #define XB_SPIN(cond, bar) do { unsigned _sp = 0; while (cond) { __builtin_amdgcn_s_sleep(1); \
;     if ((++_sp & 255u) == 0u) { if (xb_ld(&(bar)[XB_TMO])) break; if (_sp > XB_SPIN_CAP) { atomicAdd(&(bar)[XB_TMO], 1u); break; } } } } while (0)
; __device__ __forceinline__ void xcd_barrier(const XcdBarrier& b) {
;     ...
;             else XB_SPIN(xb_ld(&bar[XB_TOPGEN]) == tg, bar);
.LBB0_828:
	s_and_b32 s5, s4, 0xff
	s_mov_b64 s[56:57], -1
	s_cmp_lg_u32 s5, 0
	s_mov_b64 s[60:61], -1
	s_sleep 0
	s_cbranch_scc0 .LBB0_831
	s_and_b64 vcc, exec, s[60:61]
	s_cbranch_vccz .LBB0_827

; __device__ __forceinline__ unsigned xb_ld(unsigned* p)              { return __hip_atomic_load(p, __ATOMIC_RELAXED, __HIP_MEMORY_SCOPE_AGENT); }
; #define XB_SPIN(cond, bar) do { unsigned _sp = 0; while (cond) { __builtin_amdgcn_s_sleep(1); \
;     if ((++_sp & 255u) == 0u) { if (xb_ld(&(bar)[XB_TMO])) break; if (_sp > XB_SPIN_CAP) { atomicAdd(&(bar)[XB_TMO], 1u); break; } } } } while (0)
; __device__ __forceinline__ void xcd_barrier(const XcdBarrier& b) {
;     ...
;             XB_SPIN(xb_ld(&bar[XB_XGEN(b.x)]) == gen, bar);
.LBB0_845:
	s_and_b32 s5, s4, 0xff
	s_cmp_lg_u32 s5, 0
	s_mov_b64 s[58:59], -1
	s_sleep 0
	s_cbranch_scc0 .LBB0_848
	s_mov_b64 s[60:61], -1
	s_and_b64 vcc, exec, s[58:59]
	s_cbranch_vccz .LBB0_844

; __device__ __forceinline__ unsigned xb_ld(unsigned* p)              { return __hip_atomic_load(p, __ATOMIC_RELAXED, __HIP_MEMORY_SCOPE_AGENT); }
; __device__ __forceinline__ void xcd_barrier_complete(unsigned* bar, unsigned x, unsigned& nloc, unsigned& nx) {
;     ...
;     for (;;) {
;         sum = 0u; cnt = 0u; mine = 0u;
; #pragma unroll
;         for (unsigned j = 0; j < 16; ++j) { const unsigned c = xb_ld(&bar[XB_XCNT(j)]); sum += c; cnt += (c > 0u) ? 1u : 0u; mine = (j == x) ? c : mine; }
;         if (sum == G) break;
;         __builtin_amdgcn_s_sleep(1);
;         if ((++sp & 255u) == 0u) { if (xb_ld(&bar[XB_TMO])) break; if (sp > XB_SPIN_CAP) { atomicAdd(&bar[XB_TMO], 1u); break; } }
;     }
.LBB0_884:
	global_load_dword v15, v16, s[8:9] sc1
	s_waitcnt lgkmcnt(0)
	global_load_dword v0, v16, s[10:11] sc1
	global_load_dword v1, v16, s[12:13] sc1
	global_load_dword v2, v16, s[14:15] sc1
	global_load_dword v3, v16, s[18:19] sc1
	global_load_dword v4, v16, s[48:49] sc1
	global_load_dword v5, v16, s[58:59] sc1
	global_load_dword v6, v16, s[60:61] sc1
	global_load_dword v7, v16, s[62:63] sc1
	global_load_dword v8, v16, s[66:67] sc1
	global_load_dword v9, v16, s[68:69] sc1
	global_load_dword v10, v16, s[0:1] sc1
	global_load_dword v11, v16, s[70:71] sc1
	global_load_dword v12, v16, s[52:53] sc1
	global_load_dword v13, v16, s[64:65] sc1
	global_load_dword v14, v16, s[72:73] sc1
	s_mov_b64 s[74:75], -1
	s_mov_b64 s[76:77], -1
	s_waitcnt vmcnt(14)
	v_add_u32_e32 v17, v0, v15
	s_waitcnt vmcnt(13)
	v_add_u32_e32 v17, v17, v1
	s_waitcnt vmcnt(12)
	v_add_u32_e32 v17, v17, v2
	s_waitcnt vmcnt(11)
	v_add_u32_e32 v17, v17, v3
	s_waitcnt vmcnt(10)
	v_add_u32_e32 v17, v17, v4
	s_waitcnt vmcnt(9)
	v_add_u32_e32 v17, v17, v5
	s_waitcnt vmcnt(8)
	v_add_u32_e32 v17, v17, v6
	s_waitcnt vmcnt(7)
	v_add_u32_e32 v17, v17, v7
	s_waitcnt vmcnt(6)
	v_add_u32_e32 v17, v17, v8
	s_waitcnt vmcnt(5)
	v_add_u32_e32 v17, v17, v9
	s_waitcnt vmcnt(4)
	v_add_u32_e32 v17, v17, v10
	s_waitcnt vmcnt(3)
	v_add_u32_e32 v17, v17, v11
	s_waitcnt vmcnt(2)
	v_add_u32_e32 v17, v17, v12
	s_waitcnt vmcnt(1)
	v_add_u32_e32 v17, v17, v13
	s_waitcnt vmcnt(0)
	v_add_u32_e32 v17, v17, v14
	v_cmp_eq_u32_e32 vcc, s16, v17
	s_cbranch_vccnz .LBB0_883
	s_and_b32 s20, s17, 0xff
	s_cmp_eq_u32 s20, 0
	s_mov_b64 s[78:79], -1
	s_sleep 0
	s_cbranch_scc1 .LBB0_888
	s_and_b64 vcc, exec, s[78:79]
	s_cbranch_vccz .LBB0_883

; __device__ __forceinline__ unsigned xb_ld(unsigned* p)              { return __hip_atomic_load(p, __ATOMIC_RELAXED, __HIP_MEMORY_SCOPE_AGENT); }
; #define XB_SPIN(cond, bar) do { unsigned _sp = 0; while (cond) { __builtin_amdgcn_s_sleep(1); \
;     if ((++_sp & 255u) == 0u) { if (xb_ld(&(bar)[XB_TMO])) break; if (_sp > XB_SPIN_CAP) { atomicAdd(&(bar)[XB_TMO], 1u); break; } } } } while (0)
; __device__ __forceinline__ void xcd_barrier(const XcdBarrier& b) {
;     ...
;             else XB_SPIN(xb_ld(&bar[XB_TOPGEN]) == tg, bar);
.LBB0_902:
	s_and_b32 s17, s16, 0xff
	s_mov_b64 s[48:49], -1
	s_cmp_lg_u32 s17, 0
	s_mov_b64 s[58:59], -1
	s_sleep 0
	s_cbranch_scc0 .LBB0_905
	s_and_b64 vcc, exec, s[58:59]
	s_cbranch_vccz .LBB0_901

; __device__ __forceinline__ unsigned xb_ld(unsigned* p)              { return __hip_atomic_load(p, __ATOMIC_RELAXED, __HIP_MEMORY_SCOPE_AGENT); }
; #define XB_SPIN(cond, bar) do { unsigned _sp = 0; while (cond) { __builtin_amdgcn_s_sleep(1); \
;     if ((++_sp & 255u) == 0u) { if (xb_ld(&(bar)[XB_TMO])) break; if (_sp > XB_SPIN_CAP) { atomicAdd(&(bar)[XB_TMO], 1u); break; } } } } while (0)
; __device__ __forceinline__ void xcd_barrier(const XcdBarrier& b) {
;     ...
;             XB_SPIN(xb_ld(&bar[XB_XGEN(b.x)]) == gen, bar);
.LBB0_919:
	s_and_b32 s17, s16, 0xff
	s_cmp_lg_u32 s17, 0
	s_mov_b64 s[52:53], -1
	s_sleep 0
	s_cbranch_scc0 .LBB0_922
	s_mov_b64 s[58:59], -1
	s_and_b64 vcc, exec, s[52:53]
	s_cbranch_vccz .LBB0_918

;     __device__ __forceinline__ void operator()(const f32x4 (&acc)[2][2][4][2], const Unit& u, int wr, int wc, int fr, int fq) const {
;     ...
;             while ((unsigned)__builtin_amdgcn_readfirstlane(__hip_atomic_load(f, __ATOMIC_RELAXED, __HIP_MEMORY_SCOPE_AGENT)) < 8u) { __builtin_amdgcn_s_sleep(2); if (++sp > (1u << 20)) break; }
;             __builtin_amdgcn_fence(__ATOMIC_ACQUIRE, "agent");
;             asm volatile("s_waitcnt vmcnt(0)" ::: "memory");
.Lp7x_poll:
	v_mov_b32_e32 v128, 0
	global_load_dword v128, v128, s[100:101] sc1
	s_waitcnt vmcnt(0)
	v_readfirstlane_b32 s98, v128
	s_cmp_gt_u32 s98, 7
	s_cbranch_scc1 .Lp7x_got
	s_sleep 0
	s_branch .Lp7x_poll

;     __device__ __forceinline__ void operator()(const f32x4 (&acc)[2][2][4][2], const Unit& u, int wr, int wc, int fr, int fq) const {
;     ...
;             while ((unsigned)__builtin_amdgcn_readfirstlane(__hip_atomic_load(f, __ATOMIC_RELAXED, __HIP_MEMORY_SCOPE_AGENT)) < 8u) { __builtin_amdgcn_s_sleep(2); if (++sp > (1u << 20)) break; }
.LBB0_970:
	global_load_dword v128, v147, s[0:1] sc1
	s_mov_b64 s[48:49], -1
	s_waitcnt vmcnt(0)
	v_readfirstlane_b32 s33, v128
	s_cmp_gt_u32 s33, 7
	s_cbranch_scc1 .LBB0_969
	s_add_i32 s6, s6, -1
	s_cmp_eq_u32 s6, 0
	s_cselect_b64 s[48:49], -1, 0
	s_sleep 0
	s_branch .LBB0_969

; __device__ __forceinline__ unsigned xb_ld(unsigned* p)              { return __hip_atomic_load(p, __ATOMIC_RELAXED, __HIP_MEMORY_SCOPE_AGENT); }
; __device__ __forceinline__ void xcd_barrier_complete(unsigned* bar, unsigned x, unsigned& nloc, unsigned& nx) {
;     ...
;     for (;;) {
;         sum = 0u; cnt = 0u; mine = 0u;
; #pragma unroll
;         for (unsigned j = 0; j < 16; ++j) { const unsigned c = xb_ld(&bar[XB_XCNT(j)]); sum += c; cnt += (c > 0u) ? 1u : 0u; mine = (j == x) ? c : mine; }
;         if (sum == G) break;
;         __builtin_amdgcn_s_sleep(1);
;         if ((++sp & 255u) == 0u) { if (xb_ld(&bar[XB_TMO])) break; if (sp > XB_SPIN_CAP) { atomicAdd(&bar[XB_TMO], 1u); break; } }
;     }
.LBB0_990:
	global_load_dword v15, v16, s[12:13] sc1
	s_waitcnt lgkmcnt(0)
	global_load_dword v0, v16, s[14:15] sc1
	global_load_dword v1, v16, s[18:19] sc1
	global_load_dword v2, v16, s[46:47] sc1
	global_load_dword v3, v16, s[48:49] sc1
	global_load_dword v4, v16, s[54:55] sc1
	global_load_dword v5, v16, s[56:57] sc1
	global_load_dword v6, v16, s[58:59] sc1
	global_load_dword v7, v16, s[60:61] sc1
	global_load_dword v8, v16, s[62:63] sc1
	global_load_dword v9, v16, s[66:67] sc1
	global_load_dword v10, v16, s[0:1] sc1
	global_load_dword v11, v16, s[68:69] sc1
	global_load_dword v12, v16, s[52:53] sc1
	global_load_dword v13, v16, s[64:65] sc1
	global_load_dword v14, v16, s[70:71] sc1
	s_mov_b64 s[72:73], -1
	s_mov_b64 s[74:75], -1
	s_waitcnt vmcnt(14)
	v_add_u32_e32 v17, v0, v15
	s_waitcnt vmcnt(13)
	v_add_u32_e32 v17, v17, v1
	s_waitcnt vmcnt(12)
	v_add_u32_e32 v17, v17, v2
	s_waitcnt vmcnt(11)
	v_add_u32_e32 v17, v17, v3
	s_waitcnt vmcnt(10)
	v_add_u32_e32 v17, v17, v4
	s_waitcnt vmcnt(9)
	v_add_u32_e32 v17, v17, v5
	s_waitcnt vmcnt(8)
	v_add_u32_e32 v17, v17, v6
	s_waitcnt vmcnt(7)
	v_add_u32_e32 v17, v17, v7
	s_waitcnt vmcnt(6)
	v_add_u32_e32 v17, v17, v8
	s_waitcnt vmcnt(5)
	v_add_u32_e32 v17, v17, v9
	s_waitcnt vmcnt(4)
	v_add_u32_e32 v17, v17, v10
	s_waitcnt vmcnt(3)
	v_add_u32_e32 v17, v17, v11
	s_waitcnt vmcnt(2)
	v_add_u32_e32 v17, v17, v12
	s_waitcnt vmcnt(1)
	v_add_u32_e32 v17, v17, v13
	s_waitcnt vmcnt(0)
	v_add_u32_e32 v17, v17, v14
	v_cmp_eq_u32_e32 vcc, s4, v17
	s_cbranch_vccnz .LBB0_989
	s_and_b32 s16, s5, 0xff
	s_cmp_eq_u32 s16, 0
	s_mov_b64 s[76:77], -1
	s_sleep 0
	s_cbranch_scc1 .LBB0_994
	s_and_b64 vcc, exec, s[76:77]
	s_cbranch_vccz .LBB0_989

; __device__ __forceinline__ unsigned xb_ld(unsigned* p)              { return __hip_atomic_load(p, __ATOMIC_RELAXED, __HIP_MEMORY_SCOPE_AGENT); }
; #define XB_SPIN(cond, bar) do { unsigned _sp = 0; while (cond) { __builtin_amdgcn_s_sleep(1); \
;     if ((++_sp & 255u) == 0u) { if (xb_ld(&(bar)[XB_TMO])) break; if (_sp > XB_SPIN_CAP) { atomicAdd(&(bar)[XB_TMO], 1u); break; } } } } while (0)
; __device__ __forceinline__ void xcd_barrier(const XcdBarrier& b) {
;     ...
;             else XB_SPIN(xb_ld(&bar[XB_TOPGEN]) == tg, bar);
.LBB0_1008:
	s_and_b32 s5, s4, 0xff
	s_mov_b64 s[52:53], -1
	s_cmp_lg_u32 s5, 0
	s_mov_b64 s[56:57], -1
	s_sleep 0
	s_cbranch_scc0 .LBB0_1011
	s_and_b64 vcc, exec, s[56:57]
	s_cbranch_vccz .LBB0_1007

; __device__ __forceinline__ unsigned xb_ld(unsigned* p)              { return __hip_atomic_load(p, __ATOMIC_RELAXED, __HIP_MEMORY_SCOPE_AGENT); }
; #define XB_SPIN(cond, bar) do { unsigned _sp = 0; while (cond) { __builtin_amdgcn_s_sleep(1); \
;     if ((++_sp & 255u) == 0u) { if (xb_ld(&(bar)[XB_TMO])) break; if (_sp > XB_SPIN_CAP) { atomicAdd(&(bar)[XB_TMO], 1u); break; } } } } while (0)
; __device__ __forceinline__ void xcd_barrier(const XcdBarrier& b) {
;     ...
;             XB_SPIN(xb_ld(&bar[XB_XGEN(b.x)]) == gen, bar);
.LBB0_1025:
	s_and_b32 s5, s4, 0xff
	s_cmp_lg_u32 s5, 0
	s_mov_b64 s[54:55], -1
	s_sleep 0
	s_cbranch_scc0 .LBB0_1028
	s_mov_b64 s[56:57], -1
	s_and_b64 vcc, exec, s[54:55]
	s_cbranch_vccz .LBB0_1024

; __device__ __forceinline__ unsigned xb_ld(unsigned* p)              { return __hip_atomic_load(p, __ATOMIC_RELAXED, __HIP_MEMORY_SCOPE_AGENT); }
; __device__ __forceinline__ void xcd_barrier_complete(unsigned* bar, unsigned x, unsigned& nloc, unsigned& nx) {
;     ...
;     for (;;) {
;         sum = 0u; cnt = 0u; mine = 0u;
; #pragma unroll
;         for (unsigned j = 0; j < 16; ++j) { const unsigned c = xb_ld(&bar[XB_XCNT(j)]); sum += c; cnt += (c > 0u) ? 1u : 0u; mine = (j == x) ? c : mine; }
;         if (sum == G) break;
;         __builtin_amdgcn_s_sleep(1);
;         if ((++sp & 255u) == 0u) { if (xb_ld(&bar[XB_TMO])) break; if (sp > XB_SPIN_CAP) { atomicAdd(&bar[XB_TMO], 1u); break; } }
;     }
.LBB0_1062:
	global_load_dword v15, v16, s[14:15] sc1
	s_waitcnt lgkmcnt(0)
	global_load_dword v0, v16, s[18:19] sc1
	global_load_dword v1, v16, s[46:47] sc1
	global_load_dword v2, v16, s[48:49] sc1
	global_load_dword v3, v16, s[54:55] sc1
	global_load_dword v4, v16, s[56:57] sc1
	global_load_dword v5, v16, s[58:59] sc1
	global_load_dword v6, v16, s[60:61] sc1
	global_load_dword v7, v16, s[62:63] sc1
	global_load_dword v8, v16, s[66:67] sc1
	global_load_dword v9, v16, s[68:69] sc1
	global_load_dword v10, v16, s[0:1] sc1
	global_load_dword v11, v16, s[70:71] sc1
	global_load_dword v12, v16, s[52:53] sc1
	global_load_dword v13, v16, s[64:65] sc1
	global_load_dword v14, v16, s[72:73] sc1
	s_mov_b64 s[74:75], -1
	s_mov_b64 s[76:77], -1
	s_waitcnt vmcnt(14)
	v_add_u32_e32 v17, v0, v15
	s_waitcnt vmcnt(13)
	v_add_u32_e32 v17, v17, v1
	s_waitcnt vmcnt(12)
	v_add_u32_e32 v17, v17, v2
	s_waitcnt vmcnt(11)
	v_add_u32_e32 v17, v17, v3
	s_waitcnt vmcnt(10)
	v_add_u32_e32 v17, v17, v4
	s_waitcnt vmcnt(9)
	v_add_u32_e32 v17, v17, v5
	s_waitcnt vmcnt(8)
	v_add_u32_e32 v17, v17, v6
	s_waitcnt vmcnt(7)
	v_add_u32_e32 v17, v17, v7
	s_waitcnt vmcnt(6)
	v_add_u32_e32 v17, v17, v8
	s_waitcnt vmcnt(5)
	v_add_u32_e32 v17, v17, v9
	s_waitcnt vmcnt(4)
	v_add_u32_e32 v17, v17, v10
	s_waitcnt vmcnt(3)
	v_add_u32_e32 v17, v17, v11
	s_waitcnt vmcnt(2)
	v_add_u32_e32 v17, v17, v12
	s_waitcnt vmcnt(1)
	v_add_u32_e32 v17, v17, v13
	s_waitcnt vmcnt(0)
	v_add_u32_e32 v17, v17, v14
	v_cmp_eq_u32_e32 vcc, s4, v17
	s_cbranch_vccnz .LBB0_1061
	s_and_b32 s16, s5, 0xff
	s_cmp_eq_u32 s16, 0
	s_mov_b64 s[78:79], -1
	s_sleep 0
	s_cbranch_scc1 .LBB0_1066
	s_and_b64 vcc, exec, s[78:79]
	s_cbranch_vccz .LBB0_1061

.LBB0_1080:
	s_and_b32 s5, s4, 0xff
	s_mov_b64 s[54:55], -1
	s_cmp_lg_u32 s5, 0
	s_mov_b64 s[58:59], -1
	s_sleep 0
	s_cbranch_scc0 .LBB0_1083
	s_and_b64 vcc, exec, s[58:59]
	s_cbranch_vccz .LBB0_1079

; __device__ __forceinline__ unsigned xb_ld(unsigned* p)              { return __hip_atomic_load(p, __ATOMIC_RELAXED, __HIP_MEMORY_SCOPE_AGENT); }
; __device__ __forceinline__ void xcd_barrier_complete(unsigned* bar, unsigned x, unsigned& nloc, unsigned& nx) {
;     ...
;     for (;;) {
;         sum = 0u; cnt = 0u; mine = 0u;
; #pragma unroll
;         for (unsigned j = 0; j < 16; ++j) { const unsigned c = xb_ld(&bar[XB_XCNT(j)]); sum += c; cnt += (c > 0u) ? 1u : 0u; mine = (j == x) ? c : mine; }
;         if (sum == G) break;
;         __builtin_amdgcn_s_sleep(1);
;         if ((++sp & 255u) == 0u) { if (xb_ld(&bar[XB_TMO])) break; if (sp > XB_SPIN_CAP) { atomicAdd(&bar[XB_TMO], 1u); break; } }
;     }
.LBB0_1144:
	global_load_dword v15, v16, s[12:13] sc1
	s_waitcnt lgkmcnt(0)
	global_load_dword v0, v16, s[14:15] sc1
	global_load_dword v1, v16, s[18:19] sc1
	global_load_dword v2, v16, s[36:37] sc1
	global_load_dword v3, v16, s[38:39] sc1
	global_load_dword v4, v16, s[46:47] sc1
	global_load_dword v5, v16, s[48:49] sc1
	global_load_dword v6, v16, s[54:55] sc1
	global_load_dword v7, v16, s[56:57] sc1
	global_load_dword v8, v16, s[58:59] sc1
	global_load_dword v9, v16, s[60:61] sc1
	global_load_dword v10, v16, s[0:1] sc1
	global_load_dword v11, v16, s[62:63] sc1
	global_load_dword v12, v16, s[52:53] sc1
	global_load_dword v13, v16, s[64:65] sc1
	global_load_dword v14, v16, s[66:67] sc1
	s_mov_b64 s[68:69], -1
	s_mov_b64 s[70:71], -1
	s_waitcnt vmcnt(14)
	v_add_u32_e32 v17, v0, v15
	s_waitcnt vmcnt(13)
	v_add_u32_e32 v17, v17, v1
	s_waitcnt vmcnt(12)
	v_add_u32_e32 v17, v17, v2
	s_waitcnt vmcnt(11)
	v_add_u32_e32 v17, v17, v3
	s_waitcnt vmcnt(10)
	v_add_u32_e32 v17, v17, v4
	s_waitcnt vmcnt(9)
	v_add_u32_e32 v17, v17, v5
	s_waitcnt vmcnt(8)
	v_add_u32_e32 v17, v17, v6
	s_waitcnt vmcnt(7)
	v_add_u32_e32 v17, v17, v7
	s_waitcnt vmcnt(6)
	v_add_u32_e32 v17, v17, v8
	s_waitcnt vmcnt(5)
	v_add_u32_e32 v17, v17, v9
	s_waitcnt vmcnt(4)
	v_add_u32_e32 v17, v17, v10
	s_waitcnt vmcnt(3)
	v_add_u32_e32 v17, v17, v11
	s_waitcnt vmcnt(2)
	v_add_u32_e32 v17, v17, v12
	s_waitcnt vmcnt(1)
	v_add_u32_e32 v17, v17, v13
	s_waitcnt vmcnt(0)
	v_add_u32_e32 v17, v17, v14
	v_cmp_eq_u32_e32 vcc, s4, v17
	s_cbranch_vccnz .LBB0_1143
	s_and_b32 s16, s5, 0xff
	s_cmp_eq_u32 s16, 0
	s_mov_b64 s[72:73], -1
	s_sleep 0
	s_cbranch_scc1 .LBB0_1148
	s_and_b64 vcc, exec, s[72:73]
	s_cbranch_vccz .LBB0_1143

.LBB0_1162:
	s_and_b32 s5, s4, 0xff
	s_mov_b64 s[46:47], -1
	s_cmp_lg_u32 s5, 0
	s_mov_b64 s[52:53], -1
	s_sleep 0
	s_cbranch_scc0 .LBB0_1165
	s_and_b64 vcc, exec, s[52:53]
	s_cbranch_vccz .LBB0_1161

.LBB0_1179:
	s_and_b32 s5, s4, 0xff
	s_cmp_lg_u32 s5, 0
	s_mov_b64 s[48:49], -1
	s_sleep 0
	s_cbranch_scc0 .LBB0_1182
	s_mov_b64 s[52:53], -1
	s_and_b64 vcc, exec, s[48:49]
	s_cbranch_vccz .LBB0_1178

; __device__ __forceinline__ unsigned xb_ld(unsigned* p)              { return __hip_atomic_load(p, __ATOMIC_RELAXED, __HIP_MEMORY_SCOPE_AGENT); }
; __device__ __forceinline__ void xcd_barrier_complete(unsigned* bar, unsigned x, unsigned& nloc, unsigned& nx) {
;     ...
;     for (;;) {
;         sum = 0u; cnt = 0u; mine = 0u;
; #pragma unroll
;         for (unsigned j = 0; j < 16; ++j) { const unsigned c = xb_ld(&bar[XB_XCNT(j)]); sum += c; cnt += (c > 0u) ? 1u : 0u; mine = (j == x) ? c : mine; }
;         if (sum == G) break;
;         __builtin_amdgcn_s_sleep(1);
;         if ((++sp & 255u) == 0u) { if (xb_ld(&bar[XB_TMO])) break; if (sp > XB_SPIN_CAP) { atomicAdd(&bar[XB_TMO], 1u); break; } }
;     }
.LBB0_1241:
	global_load_dword v15, v16, s[10:11] sc1
	s_waitcnt lgkmcnt(0)
	global_load_dword v0, v16, s[12:13] sc1
	global_load_dword v1, v16, s[14:15] sc1
	global_load_dword v2, v16, s[22:23] sc1
	global_load_dword v3, v16, s[28:29] sc1
	global_load_dword v4, v16, s[36:37] sc1
	global_load_dword v5, v16, s[38:39] sc1
	global_load_dword v6, v16, s[42:43] sc1
	global_load_dword v7, v16, s[46:47] sc1
	global_load_dword v8, v16, s[48:49] sc1
	global_load_dword v9, v16, s[52:53] sc1
	global_load_dword v10, v16, s[0:1] sc1
	global_load_dword v11, v16, s[54:55] sc1
	global_load_dword v12, v16, s[56:57] sc1
	global_load_dword v13, v16, s[58:59] sc1
	global_load_dword v14, v16, s[60:61] sc1
	s_mov_b64 s[62:63], -1
	s_mov_b64 s[64:65], -1
	s_waitcnt vmcnt(14)
	v_add_u32_e32 v17, v0, v15
	s_waitcnt vmcnt(13)
	v_add_u32_e32 v17, v17, v1
	s_waitcnt vmcnt(12)
	v_add_u32_e32 v17, v17, v2
	s_waitcnt vmcnt(11)
	v_add_u32_e32 v17, v17, v3
	s_waitcnt vmcnt(10)
	v_add_u32_e32 v17, v17, v4
	s_waitcnt vmcnt(9)
	v_add_u32_e32 v17, v17, v5
	s_waitcnt vmcnt(8)
	v_add_u32_e32 v17, v17, v6
	s_waitcnt vmcnt(7)
	v_add_u32_e32 v17, v17, v7
	s_waitcnt vmcnt(6)
	v_add_u32_e32 v17, v17, v8
	s_waitcnt vmcnt(5)
	v_add_u32_e32 v17, v17, v9
	s_waitcnt vmcnt(4)
	v_add_u32_e32 v17, v17, v10
	s_waitcnt vmcnt(3)
	v_add_u32_e32 v17, v17, v11
	s_waitcnt vmcnt(2)
	v_add_u32_e32 v17, v17, v12
	s_waitcnt vmcnt(1)
	v_add_u32_e32 v17, v17, v13
	s_waitcnt vmcnt(0)
	v_add_u32_e32 v17, v17, v14
	v_cmp_eq_u32_e32 vcc, s4, v17
	s_cbranch_vccnz .LBB0_1240
	s_and_b32 s16, s5, 0xff
	s_cmp_eq_u32 s16, 0
	s_mov_b64 s[66:67], -1
	s_sleep 0
	s_cbranch_scc1 .LBB0_1245
	s_and_b64 vcc, exec, s[66:67]
	s_cbranch_vccz .LBB0_1240

.LBB0_1259:
	s_and_b32 s5, s4, 0xff
	s_mov_b64 s[36:37], -1
	s_cmp_lg_u32 s5, 0
	s_mov_b64 s[42:43], -1
	s_sleep 0
	s_cbranch_scc0 .LBB0_1262
	s_and_b64 vcc, exec, s[42:43]
	s_cbranch_vccz .LBB0_1258

.LBB0_1276:
	s_and_b32 s5, s4, 0xff
	s_cmp_lg_u32 s5, 0
	s_mov_b64 s[38:39], -1
	s_sleep 0
	s_cbranch_scc0 .LBB0_1279
	s_mov_b64 s[42:43], -1
	s_and_b64 vcc, exec, s[38:39]
	s_cbranch_vccz .LBB0_1275

; __device__ __forceinline__ unsigned xb_ld(unsigned* p)              { return __hip_atomic_load(p, __ATOMIC_RELAXED, __HIP_MEMORY_SCOPE_AGENT); }
; __device__ __forceinline__ void xcd_barrier_complete(unsigned* bar, unsigned x, unsigned& nloc, unsigned& nx) {
;     ...
;     for (;;) {
;         sum = 0u; cnt = 0u; mine = 0u;
; #pragma unroll
;         for (unsigned j = 0; j < 16; ++j) { const unsigned c = xb_ld(&bar[XB_XCNT(j)]); sum += c; cnt += (c > 0u) ? 1u : 0u; mine = (j == x) ? c : mine; }
;         if (sum == G) break;
;         __builtin_amdgcn_s_sleep(1);
;         if ((++sp & 255u) == 0u) { if (xb_ld(&bar[XB_TMO])) break; if (sp > XB_SPIN_CAP) { atomicAdd(&bar[XB_TMO], 1u); break; } }
;     }
.LBB0_1322:
	global_load_dword v15, v16, s[10:11] sc1
	s_waitcnt lgkmcnt(0)
	global_load_dword v0, v16, s[12:13] sc1
	global_load_dword v1, v16, s[14:15] sc1
	global_load_dword v2, v16, s[18:19] sc1
	global_load_dword v3, v16, s[22:23] sc1
	global_load_dword v4, v16, s[24:25] sc1
	global_load_dword v5, v16, s[26:27] sc1
	global_load_dword v6, v16, s[28:29] sc1
	global_load_dword v7, v16, s[36:37] sc1
	global_load_dword v8, v16, s[38:39] sc1
	global_load_dword v9, v16, s[42:43] sc1
	global_load_dword v10, v16, s[0:1] sc1
	global_load_dword v11, v16, s[46:47] sc1
	global_load_dword v12, v16, s[48:49] sc1
	global_load_dword v13, v16, s[50:51] sc1
	global_load_dword v14, v16, s[52:53] sc1
	s_mov_b64 s[54:55], -1
	s_mov_b64 s[56:57], -1
	s_waitcnt vmcnt(14)
	v_add_u32_e32 v17, v0, v15
	s_waitcnt vmcnt(13)
	v_add_u32_e32 v17, v17, v1
	s_waitcnt vmcnt(12)
	v_add_u32_e32 v17, v17, v2
	s_waitcnt vmcnt(11)
	v_add_u32_e32 v17, v17, v3
	s_waitcnt vmcnt(10)
	v_add_u32_e32 v17, v17, v4
	s_waitcnt vmcnt(9)
	v_add_u32_e32 v17, v17, v5
	s_waitcnt vmcnt(8)
	v_add_u32_e32 v17, v17, v6
	s_waitcnt vmcnt(7)
	v_add_u32_e32 v17, v17, v7
	s_waitcnt vmcnt(6)
	v_add_u32_e32 v17, v17, v8
	s_waitcnt vmcnt(5)
	v_add_u32_e32 v17, v17, v9
	s_waitcnt vmcnt(4)
	v_add_u32_e32 v17, v17, v10
	s_waitcnt vmcnt(3)
	v_add_u32_e32 v17, v17, v11
	s_waitcnt vmcnt(2)
	v_add_u32_e32 v17, v17, v12
	s_waitcnt vmcnt(1)
	v_add_u32_e32 v17, v17, v13
	s_waitcnt vmcnt(0)
	v_add_u32_e32 v17, v17, v14
	v_cmp_eq_u32_e32 vcc, s3, v17
	s_cbranch_vccnz .LBB0_1321
	s_and_b32 s5, s4, 0xff
	s_cmp_eq_u32 s5, 0
	s_mov_b64 s[58:59], -1
	s_sleep 0
	s_cbranch_scc1 .LBB0_1326
	s_and_b64 vcc, exec, s[58:59]
	s_cbranch_vccz .LBB0_1321

.LBB0_1340:
	s_and_b32 s4, s3, 0xff
	s_mov_b64 s[24:25], -1
	s_cmp_lg_u32 s4, 0
	s_mov_b64 s[28:29], -1
	s_sleep 0
	s_cbranch_scc0 .LBB0_1343
	s_and_b64 vcc, exec, s[28:29]
	s_cbranch_vccz .LBB0_1339

.LBB0_1357:
	s_and_b32 s4, s3, 0xff
	s_cmp_lg_u32 s4, 0
	s_mov_b64 s[26:27], -1
	s_sleep 0
	s_cbranch_scc0 .LBB0_1360
	s_mov_b64 s[28:29], -1
	s_and_b64 vcc, exec, s[26:27]
	s_cbranch_vccz .LBB0_1356

; __device__ __forceinline__ unsigned xb_ld(unsigned* p)              { return __hip_atomic_load(p, __ATOMIC_RELAXED, __HIP_MEMORY_SCOPE_AGENT); }
; __device__ __forceinline__ void xcd_barrier_complete(unsigned* bar, unsigned x, unsigned& nloc, unsigned& nx) {
;     ...
;     for (;;) {
;         sum = 0u; cnt = 0u; mine = 0u;
; #pragma unroll
;         for (unsigned j = 0; j < 16; ++j) { const unsigned c = xb_ld(&bar[XB_XCNT(j)]); sum += c; cnt += (c > 0u) ? 1u : 0u; mine = (j == x) ? c : mine; }
;         if (sum == G) break;
;         __builtin_amdgcn_s_sleep(1);
;         if ((++sp & 255u) == 0u) { if (xb_ld(&bar[XB_TMO])) break; if (sp > XB_SPIN_CAP) { atomicAdd(&bar[XB_TMO], 1u); break; } }
;     }
.LBB0_1394:
	global_load_dword v15, v16, s[4:5] sc1
	s_waitcnt lgkmcnt(0)
	global_load_dword v0, v16, s[8:9] sc1
	global_load_dword v1, v16, s[10:11] sc1
	global_load_dword v2, v16, s[12:13] sc1
	global_load_dword v3, v16, s[14:15] sc1
	global_load_dword v4, v16, s[18:19] sc1
	global_load_dword v5, v16, s[22:23] sc1
	global_load_dword v6, v16, s[24:25] sc1
	global_load_dword v7, v16, s[26:27] sc1
	global_load_dword v8, v16, s[28:29] sc1
	global_load_dword v9, v16, s[36:37] sc1
	global_load_dword v10, v16, s[38:39] sc1
	global_load_dword v11, v16, s[40:41] sc1
	global_load_dword v12, v16, s[42:43] sc1
	global_load_dword v13, v16, s[46:47] sc1
	global_load_dword v14, v16, s[48:49] sc1
	s_mov_b64 s[50:51], -1
	s_mov_b64 s[52:53], -1
	s_waitcnt vmcnt(14)
	v_add_u32_e32 v17, v0, v15
	s_waitcnt vmcnt(13)
	v_add_u32_e32 v17, v17, v1
	s_waitcnt vmcnt(12)
	v_add_u32_e32 v17, v17, v2
	s_waitcnt vmcnt(11)
	v_add_u32_e32 v17, v17, v3
	s_waitcnt vmcnt(10)
	v_add_u32_e32 v17, v17, v4
	s_waitcnt vmcnt(9)
	v_add_u32_e32 v17, v17, v5
	s_waitcnt vmcnt(8)
	v_add_u32_e32 v17, v17, v6
	s_waitcnt vmcnt(7)
	v_add_u32_e32 v17, v17, v7
	s_waitcnt vmcnt(6)
	v_add_u32_e32 v17, v17, v8
	s_waitcnt vmcnt(5)
	v_add_u32_e32 v17, v17, v9
	s_waitcnt vmcnt(4)
	v_add_u32_e32 v17, v17, v10
	s_waitcnt vmcnt(3)
	v_add_u32_e32 v17, v17, v11
	s_waitcnt vmcnt(2)
	v_add_u32_e32 v17, v17, v12
	s_waitcnt vmcnt(1)
	v_add_u32_e32 v17, v17, v13
	s_waitcnt vmcnt(0)
	v_add_u32_e32 v17, v17, v14
	v_cmp_eq_u32_e32 vcc, s16, v17
	s_cbranch_vccnz .LBB0_1393
	s_and_b32 s20, s17, 0xff
	s_cmp_eq_u32 s20, 0
	s_mov_b64 s[54:55], -1
	s_sleep 0
	s_cbranch_scc1 .LBB0_1398
	s_and_b64 vcc, exec, s[54:55]
	s_cbranch_vccz .LBB0_1393

.LBB0_1412:
	s_and_b32 s17, s16, 0xff
	s_mov_b64 s[22:23], -1
	s_cmp_lg_u32 s17, 0
	s_mov_b64 s[26:27], -1
	s_sleep 0
	s_cbranch_scc0 .LBB0_1415
	s_and_b64 vcc, exec, s[26:27]
	s_cbranch_vccz .LBB0_1411

.LBB0_1429:
	s_and_b32 s17, s16, 0xff
	s_cmp_lg_u32 s17, 0
	s_mov_b64 s[24:25], -1
	s_sleep 0
	s_cbranch_scc0 .LBB0_1432
	s_mov_b64 s[26:27], -1
	s_and_b64 vcc, exec, s[24:25]
	s_cbranch_vccz .LBB0_1428
